# grid barrier one hop shorter: last cross-XCD arriver bumps every XGEN directly, other XCD leaders poll XGEN(x) (no TOPGEN poll + re-bump)
# baseline (speedup 1.0000x reference)
; __device__ __forceinline__ unsigned xb_ld(unsigned* p)              { return __hip_atomic_load(p, __ATOMIC_RELAXED, __HIP_MEMORY_SCOPE_AGENT); }
; __device__ __forceinline__ unsigned xb_add(unsigned* p, unsigned v) { return __hip_atomic_fetch_add(p, v, __ATOMIC_RELAXED, __HIP_MEMORY_SCOPE_AGENT); }
; #define XB_SPIN(cond, bar) do { unsigned _sp = 0; while (cond) { __builtin_amdgcn_s_sleep(1); \
;     if ((++_sp & 255u) == 0u) { if (xb_ld(&(bar)[XB_TMO])) break; if (_sp > XB_SPIN_CAP) { atomicAdd(&(bar)[XB_TMO], 1u); break; } } } } while (0)
; __device__ __forceinline__ void xcd_barrier(const XcdBarrier& b) {
;     ...
;         const unsigned old = xb_add(&bar[XB_XSUB(b.x)], 1u);
;         const unsigned gen = old / nloc;
;         if (old + 1u == (gen + 1u) * nloc) {
;             __builtin_amdgcn_fence(__ATOMIC_RELEASE, "agent");
;             asm volatile("s_waitcnt vmcnt(0)" ::: "memory");
;             const unsigned og = xb_add(&bar[XB_TOP], 1u);
;             const unsigned tg = og / nx;
;             if (og + 1u == (tg + 1u) * nx) xb_add(&bar[XB_TOPGEN], 1u);
;             else XB_SPIN(xb_ld(&bar[XB_TOPGEN]) == tg, bar);
.LBB0_555:
	s_andn2_saveexec_b64 s[0:1], s[0:1]
	s_cbranch_execz .LBB0_571
	v_mov_b32_e32 v1, s48
	v_add_co_u32_e32 v2, vcc, 0x3000, v1
	v_mov_b32_e32 v1, s49
	buffer_wbl2 sc1
	s_waitcnt vmcnt(0)
	v_addc_co_u32_e32 v3, vcc, 0, v1, vcc
	v_mov_b32_e32 v1, 1
	flat_atomic_add v1, v[2:3], v1 offset:1024 sc0
	v_cvt_f32_u32_e32 v2, v0
	v_sub_u32_e32 v3, 0, v0
	s_add_u32 s0, s21, 0x2400
	s_addc_u32 s1, s20, 0
	v_rcp_iflag_f32_e32 v2, v2
	s_mov_b64 s[4:5], -1
	v_mul_f32_e32 v2, 0x4f7ffffe, v2
	v_cvt_u32_f32_e32 v2, v2
	v_mul_lo_u32 v3, v3, v2
	v_mul_hi_u32 v3, v2, v3
	v_add_u32_e32 v2, v2, v3
	s_waitcnt vmcnt(0) lgkmcnt(0)
	v_mul_hi_u32 v2, v1, v2
	v_mul_lo_u32 v4, v2, v0
	v_add_u32_e32 v3, 1, v1
	v_sub_u32_e32 v1, v1, v4
	v_add_u32_e32 v5, 1, v2
	v_cmp_ge_u32_e32 vcc, v1, v0
	v_sub_u32_e32 v4, v1, v0
	s_nop 0
	v_cndmask_b32_e32 v2, v2, v5, vcc
	v_cndmask_b32_e32 v1, v1, v4, vcc
	v_add_u32_e32 v4, 1, v2
	v_cmp_ge_u32_e32 vcc, v1, v0
	s_nop 1
	v_cndmask_b32_e32 v2, v2, v4, vcc
	v_mad_u64_u32 v[0:1], s[2:3], v0, v2, v[0:1]
	v_cmp_ne_u32_e32 vcc, v3, v0
	v_mov_b64_e32 v[0:1], s[0:1]
	s_and_saveexec_b64 s[2:3], vcc
	s_cbranch_execz .LBB0_568
	v_mov_b64_e32 v[0:1], s[0:1]
	flat_load_dword v0, v[0:1] sc1
	s_mov_b64 s[8:9], 0
	s_waitcnt vmcnt(0) lgkmcnt(0)
	v_cmp_eq_u32_e32 vcc, v0, v2
	s_and_saveexec_b64 s[6:7], vcc
	s_cbranch_execz .LBB0_567
	s_add_u32 s4, s48, 0x200
	s_addc_u32 s5, s49, 0
	s_mov_b32 s22, 1
	s_branch .LBB0_560

; __device__ __forceinline__ unsigned xb_ld(unsigned* p)              { return __hip_atomic_load(p, __ATOMIC_RELAXED, __HIP_MEMORY_SCOPE_AGENT); }
; __device__ __forceinline__ unsigned xb_add(unsigned* p, unsigned v) { return __hip_atomic_fetch_add(p, v, __ATOMIC_RELAXED, __HIP_MEMORY_SCOPE_AGENT); }
; #define XB_SPIN(cond, bar) do { unsigned _sp = 0; while (cond) { __builtin_amdgcn_s_sleep(1); \
;     if ((++_sp & 255u) == 0u) { if (xb_ld(&(bar)[XB_TMO])) break; if (_sp > XB_SPIN_CAP) { atomicAdd(&(bar)[XB_TMO], 1u); break; } } } } while (0)
; __device__ __forceinline__ void xcd_barrier(const XcdBarrier& b) {
;     ...
;         if (old + 1u == (gen + 1u) * nloc) {
;             __builtin_amdgcn_fence(__ATOMIC_RELEASE, "agent");
;             asm volatile("s_waitcnt vmcnt(0)" ::: "memory");
;             const unsigned og = xb_add(&bar[XB_TOP], 1u);
;             const unsigned tg = og / nx;
;             if (og + 1u == (tg + 1u) * nx) xb_add(&bar[XB_TOPGEN], 1u);
;             else XB_SPIN(xb_ld(&bar[XB_TOPGEN]) == tg, bar);
;             __builtin_amdgcn_fence(__ATOMIC_ACQUIRE, "agent");
;             xb_add(&bar[XB_XGEN(b.x)], 1u);
;             asm volatile("s_waitcnt vmcnt(0)" ::: "memory");
.LBB0_568:
	s_or_b64 exec, exec, s[2:3]
	s_and_saveexec_b64 s[0:1], s[4:5]
	s_cbranch_execz .LBB0_570
	v_mov_b32_e32 v2, 1
	v_readlane_b32 s94, v254, 10
	v_readlane_b32 s95, v254, 11
	s_nop 3
	v_mov_b32_e32 v0, s94
	v_mov_b32_e32 v1, s95
	v_add_co_u32_e32 v0, vcc, 0x2400, v0
	s_nop 1
	v_addc_co_u32_e32 v1, vcc, 0, v1, vcc
	flat_atomic_add v[0:1], v2
	flat_atomic_add v[0:1], v2 offset:256
	flat_atomic_add v[0:1], v2 offset:512
	flat_atomic_add v[0:1], v2 offset:768
	flat_atomic_add v[0:1], v2 offset:1024
	flat_atomic_add v[0:1], v2 offset:1280
	flat_atomic_add v[0:1], v2 offset:1536
	flat_atomic_add v[0:1], v2 offset:1792
	flat_atomic_add v[0:1], v2 offset:2048
	flat_atomic_add v[0:1], v2 offset:2304
	flat_atomic_add v[0:1], v2 offset:2560
	flat_atomic_add v[0:1], v2 offset:2816
	flat_atomic_add v[0:1], v2 offset:3072
	flat_atomic_add v[0:1], v2 offset:3328
	flat_atomic_add v[0:1], v2 offset:3584
	flat_atomic_add v[0:1], v2 offset:3840
.LBB0_570:
	s_or_b64 exec, exec, s[0:1]
	v_mov_b32_e32 v0, s21
	v_add_co_u32_e32 v0, vcc, 0x2000, v0
	v_mov_b32_e32 v1, s20
	s_nop 0
	v_addc_co_u32_e32 v1, vcc, 0, v1, vcc
	v_mov_b32_e32 v2, 1
	s_waitcnt vmcnt(0) lgkmcnt(0)
	buffer_inv sc1
	s_waitcnt vmcnt(0)

; __device__ __forceinline__ unsigned xb_ld(unsigned* p)              { return __hip_atomic_load(p, __ATOMIC_RELAXED, __HIP_MEMORY_SCOPE_AGENT); }
; __device__ __forceinline__ unsigned xb_add(unsigned* p, unsigned v) { return __hip_atomic_fetch_add(p, v, __ATOMIC_RELAXED, __HIP_MEMORY_SCOPE_AGENT); }
; #define XB_SPIN(cond, bar) do { unsigned _sp = 0; while (cond) { __builtin_amdgcn_s_sleep(1); \
;     if ((++_sp & 255u) == 0u) { if (xb_ld(&(bar)[XB_TMO])) break; if (_sp > XB_SPIN_CAP) { atomicAdd(&(bar)[XB_TMO], 1u); break; } } } } while (0)
; __device__ __forceinline__ void xcd_barrier(const XcdBarrier& b) {
;     ...
;         const unsigned old = xb_add(&bar[XB_XSUB(b.x)], 1u);
;         const unsigned gen = old / nloc;
;         if (old + 1u == (gen + 1u) * nloc) {
;             __builtin_amdgcn_fence(__ATOMIC_RELEASE, "agent");
;             asm volatile("s_waitcnt vmcnt(0)" ::: "memory");
;             const unsigned og = xb_add(&bar[XB_TOP], 1u);
;             const unsigned tg = og / nx;
;             if (og + 1u == (tg + 1u) * nx) xb_add(&bar[XB_TOPGEN], 1u);
;             else XB_SPIN(xb_ld(&bar[XB_TOPGEN]) == tg, bar);
.LBB0_2259:
	s_andn2_saveexec_b64 s[0:1], s[0:1]
	s_cbranch_execz .LBB0_2275
	v_readlane_b32 s0, v254, 10
	v_readlane_b32 s1, v254, 11
	buffer_wbl2 sc1
	v_mov_b32_e32 v1, s0
	v_add_co_u32_e32 v2, vcc, 0x3000, v1
	v_mov_b32_e32 v1, s1
	s_waitcnt vmcnt(0)
	s_nop 0
	v_addc_co_u32_e32 v3, vcc, 0, v1, vcc
	v_mov_b32_e32 v1, 1
	flat_atomic_add v1, v[2:3], v1 offset:1024 sc0
	v_cvt_f32_u32_e32 v2, v0
	v_sub_u32_e32 v3, 0, v0
	s_add_u32 s0, s21, 0x2400
	s_addc_u32 s1, s20, 0
	v_rcp_iflag_f32_e32 v2, v2
	s_mov_b64 s[4:5], -1
	v_mul_f32_e32 v2, 0x4f7ffffe, v2
	v_cvt_u32_f32_e32 v2, v2
	v_mul_lo_u32 v3, v3, v2
	v_mul_hi_u32 v3, v2, v3
	v_add_u32_e32 v2, v2, v3
	s_waitcnt vmcnt(0) lgkmcnt(0)
	v_mul_hi_u32 v2, v1, v2
	v_mul_lo_u32 v4, v2, v0
	v_add_u32_e32 v3, 1, v1
	v_sub_u32_e32 v1, v1, v4
	v_add_u32_e32 v5, 1, v2
	v_cmp_ge_u32_e32 vcc, v1, v0
	v_sub_u32_e32 v4, v1, v0
	s_nop 0
	v_cndmask_b32_e32 v2, v2, v5, vcc
	v_cndmask_b32_e32 v1, v1, v4, vcc
	v_add_u32_e32 v4, 1, v2
	v_cmp_ge_u32_e32 vcc, v1, v0
	s_nop 1
	v_cndmask_b32_e32 v2, v2, v4, vcc
	v_mad_u64_u32 v[0:1], s[2:3], v0, v2, v[0:1]
	v_cmp_ne_u32_e32 vcc, v3, v0
	v_mov_b64_e32 v[0:1], s[0:1]
	s_and_saveexec_b64 s[2:3], vcc
	s_cbranch_execz .LBB0_2272
	v_mov_b64_e32 v[0:1], s[0:1]
	flat_load_dword v0, v[0:1] sc1
	s_mov_b64 s[8:9], 0
	s_waitcnt vmcnt(0) lgkmcnt(0)
	v_cmp_eq_u32_e32 vcc, v0, v2
	s_and_saveexec_b64 s[6:7], vcc
	s_cbranch_execz .LBB0_2271
	v_readlane_b32 s4, v254, 10
	v_readlane_b32 s5, v254, 11
	s_add_u32 s4, s4, 0x200
	s_addc_u32 s5, s5, 0
	s_mov_b32 s22, 1
	s_branch .LBB0_2264
